# P8: residual input tile touched line-by-line during the K loop (one discarded dword load per half body) so the epilogue x reads hit cache
# speedup vs baseline: 1.0096x; 1.0029x over previous
;     __device__ bool next(int i, Unit& u) const {
;         const long L = (long)i * G + c; if (L >= nwg) return false;
;         int wgid = (int)L; { const int q = nwg / NXCD, r = nwg % NXCD, xcd = wgid % NXCD, off = wgid / NXCD; wgid = (xcd < r ? xcd * (q + 1) : r * (q + 1) + (xcd - r) * q) + off; }
;         const int nig = WGM * nN, gid = wgid / nig, fm = gid * WGM, gsz = (nM - fm) < WGM ? (nM - fm) : WGM;
;         u.pm = fm + ((wgid % nig) % gsz); u.pn = (wgid % nig) / gsz; return true;
;     }
; template <class Epi, bool AFTER = false>
; __device__ __forceinline__ void gemm_phase(LAS unsigned char* lds, const Gemm g, const StaticOrder& S, const Epi& E) {
;     const int tid = threadIdx.x, wid = __builtin_amdgcn_readfirstlane(tid >> 6), lane = tid & 63, wr = wid >> 2, wc = wid & 3, fr = lane & 15, fq = lane >> 4;
;     const int K = g.K, nt = K / BK;
;     unsigned voffA[2], voffB[2];
; #pragma unroll
;     for (int i = 0; i < 2; ++i) { int R, C; stage_rc(tid * 16 + i * 8192, R, C); const int Rb = (R & ~31) + perm32(R & 31);
;         voffA[i] = (unsigned)(R * K + C) * 2u; voffB[i] = (unsigned)(Rb * K + C) * 2u; }
;     const size_t kstep = (size_t)(BK * 2);
;     const size_t hstep = (size_t)HALF * K * 2;
;     const size_t tstep = 2 * hstep;
;     const unsigned ldsw = (unsigned)wid * 1024u;
;     const int aoff = lds_byte(wr * 64 + fr, fq * 8), boff = lds_byte(wc * 32 + fr, fq * 8);
;     ...
;     Unit cur, nxt; int ui = 0;
;     if (!S.next(0, cur)) return;
;     f32x4 acc[2][2][4][2];
; #pragma unroll
;     for (int a = 0; a < 2; ++a)
; #pragma unroll
;         for (int b = 0; b < 2; ++b)
; #pragma unroll
;             for (int m = 0; m < 4; ++m)
; #pragma unroll
;                 for (int n = 0; n < 2; ++n) acc[a][b][m][n] = (f32x4){0.f, 0.f, 0.f, 0.f};
;     bf16x8 At[4][2], B0[2][2], B1[2][2];
;     const char* cA = (const char*)g.A + (size_t)cur.pm * tstep; const char* cB = (const char*)g.Bt + (size_t)cur.pn * tstep;
;     PG8_STAGE(PG8_SB(0, 0), cB, voffB); PG8_STAGE(PG8_SA(0, 0), cA, voffA); PG8_STAGE(PG8_SB(0, 1), cB + hstep, voffB); PG8_STAGE(PG8_SA(0, 1), cA + hstep, voffA);
;     if (wr == 1) PG8_BAR;
;     PG8_WAIT_V(4); PG8_BAR;
;     PG8_STAGE(PG8_SB(1, 0), cB + kstep, voffB); PG8_STAGE(PG8_SA(1, 0), cA + kstep, voffA); PG8_STAGE(PG8_SB(1, 1), cB + hstep + kstep, voffB);
;     PG8_WAIT_V(6); PG8_BAR;
.LBB0_837:
	s_waitcnt vmcnt(0)
	v_lshrrev_b32_e32 v2, 1, v212
	v_and_b32_e32 v11, 24, v2
	v_lshrrev_b32_e32 v2, 5, v212
	v_and_b32_e32 v2, 4, v2
	v_bfe_u32 v3, v212, 2, 2
	v_lshlrev_b32_e32 v0, 4, v212
	v_and_b32_e32 v1, 32, v212
	v_bfe_u32 v10, v212, 2, 4
	v_or3_b32 v2, v2, v3, v11
	v_lshrrev_b32_e32 v3, 3, v212
	s_movk_i32 s5, 0x70
	s_add_i32 s2, s4, s2
	v_bitop3_b32 v8, v0, v1, 48 bitop3:0x6c
	v_and_b32_e32 v9, 64, v212
	v_and_or_b32 v4, v3, s5, v10
	s_movk_i32 s5, 0x60
	v_add_u32_e32 v12, 0x2000, v0
	s_ashr_i32 s4, s2, 31
	v_or_b32_e32 v1, v8, v9
	v_and_or_b32 v3, v3, s5, v2
	v_lshrrev_b32_e32 v0, 7, v12
	s_movk_i32 s5, 0xf0
	s_lshr_b32 s4, s4, 28
	v_lshl_or_b32 v130, v3, 11, v1
	v_and_or_b32 v3, v0, s5, v10
	s_movk_i32 s5, 0xe0
	s_add_i32 s4, s2, s4
	v_and_or_b32 v0, v0, s5, v2
	s_ashr_i32 s5, s4, 4
	s_and_b32 s4, s4, 0xfff0
	s_sub_i32 s4, s2, s4
	s_bfe_i32 s2, s4, 0x80000
	s_bfe_u32 s2, s2, 0x2000d
	s_add_i32 s8, s4, s2
	s_bfe_i32 s2, s8, 0x80000
	s_and_b32 s8, s8, 0xfc
	s_sub_i32 s4, s4, s8
	s_lshl_b32 s5, s5, 2
	s_sext_i32_i16 s2, s2
	s_sext_i32_i8 s4, s4
	s_lshr_b32 s3, s39, 8
	s_lshr_b32 s2, s2, 2
	s_add_i32 s8, s5, s4
	s_lshr_b32 s10, s39, 6
	s_ashr_i32 s9, s8, 31
	s_bfe_i64 s[12:13], s[2:3], 0x100000
	s_lshl_b32 s41, s10, 10
	s_lshl_b64 s[4:5], s[8:9], 19
	v_readlane_b32 s98, v254, 4
	v_readlane_b32 s99, v254, 5
	s_lshl_b32 s100, s8, 20
	s_add_u32 s98, s98, s100
	s_addc_u32 s99, s99, 0
	s_lshl_b32 s100, s2, 10
	s_add_u32 s98, s98, s100
	s_addc_u32 s99, s99, 0
	v_and_b32_e32 v240, 15, v212
	v_lshlrev_b32_e32 v240, 12, v240
	v_lshrrev_b32_e32 v241, 4, v212
	v_lshl_add_u32 v240, v241, 5, v240
	s_lshl_b64 s[12:13], s[12:13], 19
	s_add_u32 s30, s37, s12
	s_addc_u32 s31, s38, s13
	s_add_i32 s9, s41, 0
	s_add_i32 m0, s9, 0x10000
	v_lshl_or_b32 v134, v0, 11, v1
	global_load_lds_dwordx4 v130, s[30:31]
	s_add_i32 m0, s9, 0x12000
	s_add_u32 s28, s33, s4
	v_lshl_or_b32 v128, v4, 11, v1
	global_load_lds_dwordx4 v134, s[30:31]
	s_addc_u32 s29, s36, s5
	s_mov_b32 m0, s9
	s_add_i32 s42, s9, 0x2000
	v_lshl_or_b32 v132, v3, 11, v1
	global_load_lds_dwordx4 v128, s[28:29]
	s_mov_b32 m0, s42
	s_add_u32 s4, s30, 0x40000
	global_load_lds_dwordx4 v132, s[28:29]
	s_addc_u32 s5, s31, 0
	s_add_i32 m0, s9, 0x14000
	v_mov_b32_e32 v131, 0
	global_load_lds_dwordx4 v130, s[4:5]
	s_add_i32 m0, s9, 0x16000
	v_mov_b32_e32 v135, v131
	global_load_lds_dwordx4 v134, s[4:5]
	s_add_u32 s4, s28, 0x40000
	s_addc_u32 s5, s29, 0
	s_add_i32 s43, s9, 0x4000
	s_mov_b32 m0, s43
	s_add_i32 s44, s9, 0x6000
	global_load_lds_dwordx4 v128, s[4:5]
	s_mov_b32 m0, s44
	s_waitcnt lgkmcnt(0)
	v_mov_b32_e32 v129, v131
	global_load_lds_dwordx4 v132, s[4:5]
	v_mov_b32_e32 v133, v131
	s_mov_b32 s45, 0
	v_lshl_add_u64 v[6:7], s[30:31], 0, v[130:131]
	v_lshl_add_u64 v[4:5], s[30:31], 0, v[134:135]
	v_lshl_add_u64 v[2:3], s[28:29], 0, v[128:129]
	s_cmp_lg_u32 s3, 1
	v_lshl_add_u64 v[0:1], s[28:29], 0, v[132:133]
	s_cbranch_scc1 .LBB0_839
	s_barrier

; #define PG8_STAGE(bufoff, gbase, voff) do { _Pragma("unroll") for (int _i = 0; _i < 2; ++_i) \
;         __builtin_amdgcn_global_load_lds((const unsigned*)((const char*)(gbase) + (voff)[_i]), (LAS unsigned*)(lds + (bufoff) + ldsw + _i * 8192), 16, 0, 0); } while (0)
; #define PG8_LDA(dst, b, h) do { _Pragma("unroll") for (int m = 0; m < 4; ++m) _Pragma("unroll") for (int k = 0; k < 2; ++k) dst[m][k] = *(const LAS bf16x8*)(lds + PG8_SA(b, h) + aoff + m * 2048 + k * 1024); } while (0)
; #define PG8_LDB(dst, b, h) do { _Pragma("unroll") for (int n = 0; n < 2; ++n) _Pragma("unroll") for (int k = 0; k < 2; ++k) dst[n][k] = *(const LAS bf16x8*)(lds + PG8_SB(b, h) + boff + n * 2048 + k * 1024); } while (0)
; #define PG8_MMA(ai, bj, At, Bt) do { __builtin_amdgcn_s_setprio(1); _Pragma("unroll") for (int m = 0; m < 4; ++m) _Pragma("unroll") for (int n = 0; n < 2; ++n) _Pragma("unroll") for (int k = 0; k < 2; ++k) \
;         acc[ai][bj][m][n] = __builtin_amdgcn_mfma_f32_16x16x32_bf16(Bt[n][k], At[m][k], acc[ai][bj][m][n], 0, 0, 0); __builtin_amdgcn_s_setprio(0); } while (0)
; #define PG8_WAIT_L(n) asm volatile("s_waitcnt lgkmcnt(" #n ")" ::: "memory")
; #define PG8_BAR __builtin_amdgcn_s_barrier()
; template <class Epi, bool AFTER = false>
; __device__ __forceinline__ void gemm_phase(LAS unsigned char* lds, const Gemm g, const StaticOrder& S, const Epi& E) {
;     ...
;         const bool has_next = S.next(ui + 1, nxt);
;         const char* nA = has_next ? (const char*)g.A + (size_t)nxt.pm * tstep : cA; const char* nB = has_next ? (const char*)g.Bt + (size_t)nxt.pn * tstep : cB;
;         for (int t = 0; t < nt; t += 2) {
;             const bool last = (t == nt - 2);
;             const char* a1 = cA + (size_t)(t + 1) * kstep;
;             const char* a2 = last ? nA : cA + (size_t)(t + 2) * kstep; const char* b2 = last ? nB : cB + (size_t)(t + 2) * kstep;
;             const char* a3 = a2 + kstep; const char* b3 = b2 + kstep;
;             PG8_LDB(B0, 0, 0); PG8_SCHED; PG8_LDA(At, 0, 0); PG8_STAGE(PG8_SA(1, 1), a1 + hstep, voffA);
;             PG8_WAIT_L(8); PG8_BAR; PG8_WAIT_L(0); PG8_MMA(0, 0, At, B0); PG8_BAR; PG8_SCHED;
;             PG8_LDB(B1, 0, 1); PG8_STAGE(PG8_SB(0, 0), b2, voffB);
;             PG8_BAR; PG8_WAIT_L(0); PG8_MMA(0, 1, At, B1); PG8_BAR;
;             PG8_LDA(At, 0, 1); PG8_STAGE(PG8_SA(0, 0), a2, voffA);
.LBB0_846:
	s_ashr_i32 s23, s22, 31
	v_cmp_lt_i64_e32 vcc, s[24:25], v[140:141]
	s_lshl_b64 s[24:25], s[22:23], 19
	s_add_u32 s24, s33, s24
	s_addc_u32 s25, s36, s25
	s_and_b64 s[26:27], vcc, exec
	s_cselect_b32 s23, s25, s29
	s_cselect_b32 s56, s24, s28
	s_ashr_i32 s21, s20, 31
	s_lshl_b64 s[26:27], s[20:21], 19
	s_add_u32 s26, s37, s26
	s_addc_u32 s27, s38, s27
	s_and_b64 s[34:35], vcc, exec
	s_cselect_b32 s21, s27, s31
	s_cselect_b32 s57, s26, s30
	s_add_u32 s28, s28, 0x40080
	s_addc_u32 s29, s29, 0
	s_add_u32 s58, s30, 0x100
	s_addc_u32 s59, s31, 0
	s_mov_b32 s60, -2
	ds_read_b128 v[150:153], v147
	ds_read_b128 v[154:157], v147 offset:1024
	ds_read_b128 v[158:161], v147 offset:2048
	ds_read_b128 v[162:165], v147 offset:3072
	s_add_u32 s30, s28, 0xfffc0080
	s_addc_u32 s31, s29, -1
	s_cmp_eq_u32 s60, 12
	s_cselect_b32 s35, s23, s31
	s_cselect_b32 s34, s56, s30
	s_cselect_b32 s31, s21, s59
	s_cselect_b32 s30, s57, s58
	v_lshl_add_u64 v[198:199], s[28:29], 0, v[136:137]
	s_add_i32 m0, s9, 0xc000
	ds_read_b128 v[166:169], v148
	ds_read_b128 v[170:173], v148 offset:1024
	ds_read_b128 v[174:177], v148 offset:2048
	ds_read_b128 v[178:181], v148 offset:3072
	ds_read_b128 v[182:185], v148 offset:4096
	ds_read_b128 v[186:189], v148 offset:5120
	ds_read_b128 v[190:193], v148 offset:6144
	ds_read_b128 v[194:197], v148 offset:7168
	global_load_lds_dwordx4 v[198:199], off
	v_lshl_add_u64 v[198:199], s[28:29], 0, v[138:139]
	s_add_i32 m0, s9, 0xe000
	s_nop 0
	global_load_lds_dwordx4 v[198:199], off
	s_waitcnt lgkmcnt(8)
	s_barrier
	s_waitcnt lgkmcnt(0)
	s_setprio 1
	s_waitcnt lgkmcnt(0)
	v_mfma_f32_16x16x32_bf16 v[124:127], v[150:153], v[166:169], 0
	v_mfma_f32_16x16x32_bf16 v[120:123], v[158:161], v[166:169], 0
	v_mfma_f32_16x16x32_bf16 v[116:119], v[150:153], v[174:177], 0
	v_mfma_f32_16x16x32_bf16 v[112:115], v[158:161], v[174:177], 0
	v_mfma_f32_16x16x32_bf16 v[100:103], v[150:153], v[182:185], 0
	v_mfma_f32_16x16x32_bf16 v[96:99], v[158:161], v[182:185], 0
	v_mfma_f32_16x16x32_bf16 v[84:87], v[150:153], v[190:193], 0
	v_mfma_f32_16x16x32_bf16 v[80:83], v[158:161], v[190:193], 0
	v_mfma_f32_16x16x32_bf16 v[124:127], v[154:157], v[170:173], v[124:127]
	v_mfma_f32_16x16x32_bf16 v[120:123], v[162:165], v[170:173], v[120:123]
	v_mfma_f32_16x16x32_bf16 v[116:119], v[154:157], v[178:181], v[116:119]
	v_mfma_f32_16x16x32_bf16 v[112:115], v[162:165], v[178:181], v[112:115]
	v_mfma_f32_16x16x32_bf16 v[100:103], v[154:157], v[186:189], v[100:103]
	v_mfma_f32_16x16x32_bf16 v[96:99], v[162:165], v[186:189], v[96:99]
	v_mfma_f32_16x16x32_bf16 v[84:87], v[154:157], v[194:197], v[84:87]
	v_mfma_f32_16x16x32_bf16 v[80:83], v[162:165], v[194:197], v[80:83]
	s_setprio 0
	s_barrier
	s_add_i32 s61, s50, s41
	v_lshl_add_u64 v[210:211], s[30:31], 0, v[130:131]
	s_mov_b32 m0, s61
	ds_read_b128 v[198:201], v149
	ds_read_b128 v[202:205], v149 offset:1024
	ds_read_b128 v[206:209], v149 offset:2048
	ds_read_b128 v[214:217], v149 offset:3072
	global_load_lds_dwordx4 v[210:211], off
	v_lshl_add_u64 v[218:219], s[30:31], 0, v[134:135]
	s_add_i32 m0, s61, 0x2000
	s_nop 0
	global_load_lds_dwordx4 v[218:219], off
	s_barrier
	s_waitcnt lgkmcnt(0)
	s_setprio 1
	s_waitcnt lgkmcnt(0)
	v_mfma_f32_16x16x32_bf16 v[108:111], v[198:201], v[166:169], 0
	v_mfma_f32_16x16x32_bf16 v[104:107], v[206:209], v[166:169], 0
	v_mfma_f32_16x16x32_bf16 v[92:95], v[198:201], v[174:177], 0
	v_mfma_f32_16x16x32_bf16 v[88:91], v[206:209], v[174:177], 0
	v_mfma_f32_16x16x32_bf16 v[76:79], v[198:201], v[182:185], 0
	v_mfma_f32_16x16x32_bf16 v[72:75], v[206:209], v[182:185], 0
	v_mfma_f32_16x16x32_bf16 v[68:71], v[198:201], v[190:193], 0
	v_mfma_f32_16x16x32_bf16 v[64:67], v[206:209], v[190:193], 0
	v_mfma_f32_16x16x32_bf16 v[108:111], v[202:205], v[170:173], v[108:111]
	v_mfma_f32_16x16x32_bf16 v[104:107], v[214:217], v[170:173], v[104:107]
	v_mfma_f32_16x16x32_bf16 v[92:95], v[202:205], v[178:181], v[92:95]
	v_mfma_f32_16x16x32_bf16 v[88:91], v[214:217], v[178:181], v[88:91]
	v_mfma_f32_16x16x32_bf16 v[76:79], v[202:205], v[186:189], v[76:79]
	v_mfma_f32_16x16x32_bf16 v[72:75], v[214:217], v[186:189], v[72:75]
	v_mfma_f32_16x16x32_bf16 v[68:71], v[202:205], v[194:197], v[68:71]
	v_mfma_f32_16x16x32_bf16 v[64:67], v[214:217], v[194:197], v[64:67]
	s_setprio 0
	s_mov_b32 m0, s9
	v_lshl_add_u64 v[220:221], s[34:35], 0, v[128:129]
	s_barrier
	ds_read_b128 v[166:169], v148 offset:16384
	ds_read_b128 v[170:173], v148 offset:17408
	ds_read_b128 v[174:177], v148 offset:18432
	ds_read_b128 v[178:181], v148 offset:19456
	ds_read_b128 v[182:185], v148 offset:20480
	ds_read_b128 v[186:189], v148 offset:21504
	ds_read_b128 v[190:193], v148 offset:22528
	ds_read_b128 v[194:197], v148 offset:23552
	global_load_lds_dwordx4 v[220:221], off
	v_lshl_add_u64 v[222:223], s[34:35], 0, v[132:133]
	s_mov_b32 m0, s42
	s_nop 0
	global_load_lds_dwordx4 v[222:223], off
	s_barrier
	s_waitcnt lgkmcnt(0)
	s_setprio 1
	s_waitcnt lgkmcnt(0)
	v_mfma_f32_16x16x32_bf16 v[60:63], v[150:153], v[166:169], 0
	v_mfma_f32_16x16x32_bf16 v[56:59], v[158:161], v[166:169], 0
	v_mfma_f32_16x16x32_bf16 v[52:55], v[150:153], v[174:177], 0
	v_mfma_f32_16x16x32_bf16 v[48:51], v[158:161], v[174:177], 0
	v_mfma_f32_16x16x32_bf16 v[40:43], v[150:153], v[182:185], 0
	v_mfma_f32_16x16x32_bf16 v[32:35], v[158:161], v[182:185], 0
	v_mfma_f32_16x16x32_bf16 v[24:27], v[150:153], v[190:193], 0
	v_mfma_f32_16x16x32_bf16 v[16:19], v[158:161], v[190:193], 0
	v_mfma_f32_16x16x32_bf16 v[60:63], v[154:157], v[170:173], v[60:63]
	v_mfma_f32_16x16x32_bf16 v[56:59], v[162:165], v[170:173], v[56:59]
	v_mfma_f32_16x16x32_bf16 v[52:55], v[154:157], v[178:181], v[52:55]
	v_mfma_f32_16x16x32_bf16 v[48:51], v[162:165], v[178:181], v[48:51]
	v_mfma_f32_16x16x32_bf16 v[40:43], v[154:157], v[186:189], v[40:43]
	v_mfma_f32_16x16x32_bf16 v[32:35], v[162:165], v[186:189], v[32:35]
	v_mfma_f32_16x16x32_bf16 v[24:27], v[154:157], v[194:197], v[24:27]
	v_mfma_f32_16x16x32_bf16 v[16:19], v[162:165], v[194:197], v[16:19]
	s_setprio 0
	s_barrier
; #define PG8_STAGE(bufoff, gbase, voff) do { _Pragma("unroll") for (int _i = 0; _i < 2; ++_i) \
;         __builtin_amdgcn_global_load_lds((const unsigned*)((const char*)(gbase) + (voff)[_i]), (LAS unsigned*)(lds + (bufoff) + ldsw + _i * 8192), 16, 0, 0); } while (0)
; #define PG8_LDA(dst, b, h) do { _Pragma("unroll") for (int m = 0; m < 4; ++m) _Pragma("unroll") for (int k = 0; k < 2; ++k) dst[m][k] = *(const LAS bf16x8*)(lds + PG8_SA(b, h) + aoff + m * 2048 + k * 1024); } while (0)
; #define PG8_LDB(dst, b, h) do { _Pragma("unroll") for (int n = 0; n < 2; ++n) _Pragma("unroll") for (int k = 0; k < 2; ++k) dst[n][k] = *(const LAS bf16x8*)(lds + PG8_SB(b, h) + boff + n * 2048 + k * 1024); } while (0)
; #define PG8_MMA(ai, bj, At, Bt) do { __builtin_amdgcn_s_setprio(1); _Pragma("unroll") for (int m = 0; m < 4; ++m) _Pragma("unroll") for (int n = 0; n < 2; ++n) _Pragma("unroll") for (int k = 0; k < 2; ++k) \
;         acc[ai][bj][m][n] = __builtin_amdgcn_mfma_f32_16x16x32_bf16(Bt[n][k], At[m][k], acc[ai][bj][m][n], 0, 0, 0); __builtin_amdgcn_s_setprio(0); } while (0)
; #define PG8_WAIT_V(n) asm volatile("s_waitcnt vmcnt(" #n ")" ::: "memory")
; #define PG8_WAIT_L(n) asm volatile("s_waitcnt lgkmcnt(" #n ")" ::: "memory")
; #define PG8_BAR __builtin_amdgcn_s_barrier()
; #define PG8_SCHED __builtin_amdgcn_sched_barrier(0)
; #define PG8_LDA(dst, b, h) do { _Pragma("unroll") for (int m = 0; m < 4; ++m) _Pragma("unroll") for (int k = 0; k < 2; ++k) dst[m][k] = *(const LAS bf16x8*)(lds + PG8_SA(b, h) + aoff + m * 2048 + k * 1024); } while (0)
; #define PG8_WAIT_V(n) asm volatile("s_waitcnt vmcnt(" #n ")" ::: "memory")
; #define PG8_BAR __builtin_amdgcn_s_barrier()
; template <class Epi, bool AFTER = false>
; __device__ __forceinline__ void gemm_phase(LAS unsigned char* lds, const Gemm g, const StaticOrder& S, const Epi& E) {
;     ...
;             PG8_STAGE(PG8_SB(0, 1), b2 + hstep, voffB);
;             PG8_WAIT_V(6); PG8_BAR; PG8_MMA(1, 1, At, B1); PG8_BAR;
;             PG8_LDB(B0, 1, 0); PG8_SCHED; PG8_LDA(At, 1, 0); PG8_STAGE(PG8_SA(0, 1), a2 + hstep, voffA);
;             PG8_WAIT_L(8); PG8_BAR; PG8_WAIT_L(0); PG8_MMA(0, 0, At, B0); PG8_BAR; PG8_SCHED;
;             PG8_LDB(B1, 1, 1); PG8_STAGE(PG8_SB(1, 0), b3, voffB);
;             PG8_BAR; PG8_WAIT_L(0); PG8_MMA(0, 1, At, B1); PG8_BAR;
;             PG8_LDA(At, 1, 1); PG8_STAGE(PG8_SA(1, 0), a3, voffA);
	s_add_u32 s62, s30, 0x40000
	s_addc_u32 s63, s31, 0
	s_add_i32 s61, s51, s41
	v_lshl_add_u64 v[150:151], s[62:63], 0, v[130:131]
	s_mov_b32 m0, s61
	s_nop 0
	global_load_lds_dwordx4 v[150:151], off
	v_lshl_add_u64 v[150:151], s[62:63], 0, v[134:135]
	s_add_i32 m0, s61, 0x2000
	s_nop 0
	global_load_lds_dwordx4 v[150:151], off
	s_waitcnt vmcnt(6)
	global_load_dword v242, v240, s[98:99]
	v_add_u32_e32 v240, 0x10000, v240
	s_barrier
	s_setprio 1
	v_mfma_f32_16x16x32_bf16 v[44:47], v[198:201], v[166:169], 0
	v_mfma_f32_16x16x32_bf16 v[36:39], v[206:209], v[166:169], 0
	v_mfma_f32_16x16x32_bf16 v[28:31], v[198:201], v[174:177], 0
	v_mfma_f32_16x16x32_bf16 v[20:23], v[206:209], v[174:177], 0
	v_mfma_f32_16x16x32_bf16 v[12:15], v[198:201], v[182:185], 0
	v_mfma_f32_16x16x32_bf16 v[8:11], v[206:209], v[182:185], 0
	v_mfma_f32_16x16x32_bf16 v[4:7], v[198:201], v[190:193], 0
	v_mfma_f32_16x16x32_bf16 v[0:3], v[206:209], v[190:193], 0
	v_mfma_f32_16x16x32_bf16 v[44:47], v[202:205], v[170:173], v[44:47]
	v_mfma_f32_16x16x32_bf16 v[36:39], v[214:217], v[170:173], v[36:39]
	v_mfma_f32_16x16x32_bf16 v[28:31], v[202:205], v[178:181], v[28:31]
	v_mfma_f32_16x16x32_bf16 v[20:23], v[214:217], v[178:181], v[20:23]
	v_mfma_f32_16x16x32_bf16 v[12:15], v[202:205], v[186:189], v[12:15]
	v_mfma_f32_16x16x32_bf16 v[8:11], v[214:217], v[186:189], v[8:11]
	v_mfma_f32_16x16x32_bf16 v[4:7], v[202:205], v[194:197], v[4:7]
	v_mfma_f32_16x16x32_bf16 v[0:3], v[214:217], v[194:197], v[0:3]
	s_setprio 0
	s_add_i32 s61, 0, 0x18000
	v_add_u32_e32 v162, s61, v145
	s_barrier
	ds_read_b128 v[150:153], v162
	ds_read_b128 v[154:157], v162 offset:1024
	ds_read_b128 v[158:161], v162 offset:2048
	ds_read_b128 v[162:165], v162 offset:3072
	s_add_u32 s34, s34, 0x40000
	s_addc_u32 s35, s35, 0
	s_mov_b32 m0, s43
	v_lshl_add_u64 v[198:199], s[34:35], 0, v[128:129]
	ds_read_b128 v[166:169], v148 offset:32768
	ds_read_b128 v[170:173], v148 offset:33792
	ds_read_b128 v[174:177], v148 offset:34816
	ds_read_b128 v[178:181], v148 offset:35840
	ds_read_b128 v[182:185], v148 offset:36864
	ds_read_b128 v[186:189], v148 offset:37888
	ds_read_b128 v[190:193], v148 offset:38912
	ds_read_b128 v[194:197], v148 offset:39936
	global_load_lds_dwordx4 v[198:199], off
	v_lshl_add_u64 v[198:199], s[34:35], 0, v[132:133]
	s_mov_b32 m0, s44
	s_nop 0
	global_load_lds_dwordx4 v[198:199], off
	s_waitcnt lgkmcnt(8)
	s_barrier
	s_waitcnt lgkmcnt(0)
	s_setprio 1
	s_waitcnt lgkmcnt(0)
	v_mfma_f32_16x16x32_bf16 v[124:127], v[150:153], v[166:169], v[124:127]
	v_mfma_f32_16x16x32_bf16 v[120:123], v[158:161], v[166:169], v[120:123]
	v_mfma_f32_16x16x32_bf16 v[116:119], v[150:153], v[174:177], v[116:119]
	v_mfma_f32_16x16x32_bf16 v[112:115], v[158:161], v[174:177], v[112:115]
	v_mfma_f32_16x16x32_bf16 v[100:103], v[150:153], v[182:185], v[100:103]
	v_mfma_f32_16x16x32_bf16 v[96:99], v[158:161], v[182:185], v[96:99]
	v_mfma_f32_16x16x32_bf16 v[84:87], v[150:153], v[190:193], v[84:87]
	v_mfma_f32_16x16x32_bf16 v[80:83], v[158:161], v[190:193], v[80:83]
	v_mfma_f32_16x16x32_bf16 v[124:127], v[154:157], v[170:173], v[124:127]
	v_mfma_f32_16x16x32_bf16 v[120:123], v[162:165], v[170:173], v[120:123]
	v_mfma_f32_16x16x32_bf16 v[116:119], v[154:157], v[178:181], v[116:119]
	v_mfma_f32_16x16x32_bf16 v[112:115], v[162:165], v[178:181], v[112:115]
	v_mfma_f32_16x16x32_bf16 v[100:103], v[154:157], v[186:189], v[100:103]
	v_mfma_f32_16x16x32_bf16 v[96:99], v[162:165], v[186:189], v[96:99]
	v_mfma_f32_16x16x32_bf16 v[84:87], v[154:157], v[194:197], v[84:87]
	v_mfma_f32_16x16x32_bf16 v[80:83], v[162:165], v[194:197], v[80:83]
	s_setprio 0
	s_barrier
	s_add_i32 s34, 0, 0x1c000
	s_add_i32 s35, s61, s41
	v_add_u32_e32 v213, s34, v145
	v_lshl_add_u64 v[210:211], v[210:211], 0, s[10:11]
	s_mov_b32 m0, s35
	ds_read_b128 v[198:201], v213
	ds_read_b128 v[202:205], v213 offset:1024
	ds_read_b128 v[206:209], v213 offset:2048
	ds_read_b128 v[214:217], v213 offset:3072
	global_load_lds_dwordx4 v[210:211], off
	v_lshl_add_u64 v[210:211], v[218:219], 0, s[10:11]
	s_add_i32 m0, s35, 0x2000
	s_nop 0
	global_load_lds_dwordx4 v[210:211], off
	s_barrier
	s_waitcnt lgkmcnt(0)
	s_setprio 1
	s_waitcnt lgkmcnt(0)
	v_mfma_f32_16x16x32_bf16 v[108:111], v[198:201], v[166:169], v[108:111]
	v_mfma_f32_16x16x32_bf16 v[104:107], v[206:209], v[166:169], v[104:107]
	v_mfma_f32_16x16x32_bf16 v[92:95], v[198:201], v[174:177], v[92:95]
	v_mfma_f32_16x16x32_bf16 v[88:91], v[206:209], v[174:177], v[88:91]
	v_mfma_f32_16x16x32_bf16 v[76:79], v[198:201], v[182:185], v[76:79]
	v_mfma_f32_16x16x32_bf16 v[72:75], v[206:209], v[182:185], v[72:75]
	v_mfma_f32_16x16x32_bf16 v[68:71], v[198:201], v[190:193], v[68:71]
	v_mfma_f32_16x16x32_bf16 v[64:67], v[206:209], v[190:193], v[64:67]
	v_mfma_f32_16x16x32_bf16 v[108:111], v[202:205], v[170:173], v[108:111]
	v_mfma_f32_16x16x32_bf16 v[104:107], v[214:217], v[170:173], v[104:107]
	v_mfma_f32_16x16x32_bf16 v[92:95], v[202:205], v[178:181], v[92:95]
	v_mfma_f32_16x16x32_bf16 v[88:91], v[214:217], v[178:181], v[88:91]
	v_mfma_f32_16x16x32_bf16 v[76:79], v[202:205], v[186:189], v[76:79]
	v_mfma_f32_16x16x32_bf16 v[72:75], v[214:217], v[186:189], v[72:75]
	v_mfma_f32_16x16x32_bf16 v[68:71], v[202:205], v[194:197], v[68:71]
	v_mfma_f32_16x16x32_bf16 v[64:67], v[214:217], v[194:197], v[64:67]
	s_setprio 0
	s_mov_b32 m0, s46
	v_lshl_add_u64 v[210:211], v[220:221], 0, s[10:11]
	s_barrier
; #define PG8_STAGE(bufoff, gbase, voff) do { _Pragma("unroll") for (int _i = 0; _i < 2; ++_i) \
;         __builtin_amdgcn_global_load_lds((const unsigned*)((const char*)(gbase) + (voff)[_i]), (LAS unsigned*)(lds + (bufoff) + ldsw + _i * 8192), 16, 0, 0); } while (0)
; #define PG8_LDA(dst, b, h) do { _Pragma("unroll") for (int m = 0; m < 4; ++m) _Pragma("unroll") for (int k = 0; k < 2; ++k) dst[m][k] = *(const LAS bf16x8*)(lds + PG8_SA(b, h) + aoff + m * 2048 + k * 1024); } while (0)
; #define PG8_LDB(dst, b, h) do { _Pragma("unroll") for (int n = 0; n < 2; ++n) _Pragma("unroll") for (int k = 0; k < 2; ++k) dst[n][k] = *(const LAS bf16x8*)(lds + PG8_SB(b, h) + boff + n * 2048 + k * 1024); } while (0)
; #define PG8_WAIT_V(n) asm volatile("s_waitcnt vmcnt(" #n ")" ::: "memory")
; #define PG8_WAIT_L(n) asm volatile("s_waitcnt lgkmcnt(" #n ")" ::: "memory")
; #define PG8_BAR __builtin_amdgcn_s_barrier()
; #define PG8_SCHED __builtin_amdgcn_sched_barrier(0)
; template <class Epi, bool AFTER = false>
; __device__ __forceinline__ void gemm_phase(LAS unsigned char* lds, const Gemm g, const StaticOrder& S, const Epi& E) {
;     ...
;             PG8_LDB(B0, 0, 0); PG8_SCHED; PG8_LDA(At, 0, 0); PG8_STAGE(PG8_SA(1, 1), a1 + hstep, voffA);
;             PG8_WAIT_L(8); PG8_BAR; PG8_WAIT_L(0); PG8_MMA(0, 0, At, B0); PG8_BAR; PG8_SCHED;
;             PG8_LDB(B1, 0, 1); PG8_STAGE(PG8_SB(0, 0), b2, voffB);
;             PG8_BAR; PG8_WAIT_L(0); PG8_MMA(0, 1, At, B1); PG8_BAR;
;             PG8_LDA(At, 0, 1); PG8_STAGE(PG8_SA(0, 0), a2, voffA);
;             PG8_BAR; PG8_WAIT_L(0); PG8_MMA(1, 0, At, B0); PG8_BAR; PG8_SCHED;
;             PG8_STAGE(PG8_SB(0, 1), b2 + hstep, voffB);
;             PG8_WAIT_V(6); PG8_BAR; PG8_MMA(1, 1, At, B1); PG8_BAR;
;             PG8_LDB(B0, 1, 0); PG8_SCHED; PG8_LDA(At, 1, 0); PG8_STAGE(PG8_SA(0, 1), a2 + hstep, voffA);
;             PG8_WAIT_L(8); PG8_BAR; PG8_WAIT_L(0); PG8_MMA(0, 0, At, B0); PG8_BAR; PG8_SCHED;
;             PG8_LDB(B1, 1, 1); PG8_STAGE(PG8_SB(1, 0), b3, voffB);
;             PG8_BAR; PG8_WAIT_L(0); PG8_MMA(0, 1, At, B1); PG8_BAR;
;             PG8_LDA(At, 1, 1); PG8_STAGE(PG8_SA(1, 0), a3, voffA);
;             PG8_BAR; PG8_WAIT_L(0); PG8_MMA(1, 0, At, B0); PG8_BAR; PG8_SCHED;
;             PG8_STAGE(PG8_SB(1, 1), b3 + hstep, voffB);
;             PG8_WAIT_V(6); PG8_BAR; PG8_MMA(1, 1, At, B1); PG8_BAR;
	ds_read_b128 v[166:169], v148 offset:49152
	ds_read_b128 v[170:173], v148 offset:50176
	ds_read_b128 v[174:177], v148 offset:51200
	ds_read_b128 v[178:181], v148 offset:52224
	ds_read_b128 v[182:185], v148 offset:53248
	ds_read_b128 v[186:189], v148 offset:54272
	ds_read_b128 v[190:193], v148 offset:55296
	ds_read_b128 v[194:197], v148 offset:56320
	global_load_lds_dwordx4 v[210:211], off
	v_lshl_add_u64 v[210:211], v[222:223], 0, s[10:11]
	s_mov_b32 m0, s47
	s_nop 0
	global_load_lds_dwordx4 v[210:211], off
	s_barrier
	s_waitcnt lgkmcnt(0)
	s_setprio 1
	s_waitcnt lgkmcnt(0)
	v_mfma_f32_16x16x32_bf16 v[60:63], v[150:153], v[166:169], v[60:63]
	v_mfma_f32_16x16x32_bf16 v[56:59], v[158:161], v[166:169], v[56:59]
	v_mfma_f32_16x16x32_bf16 v[52:55], v[150:153], v[174:177], v[52:55]
	v_mfma_f32_16x16x32_bf16 v[48:51], v[158:161], v[174:177], v[48:51]
	v_mfma_f32_16x16x32_bf16 v[40:43], v[150:153], v[182:185], v[40:43]
	v_mfma_f32_16x16x32_bf16 v[32:35], v[158:161], v[182:185], v[32:35]
	v_mfma_f32_16x16x32_bf16 v[24:27], v[150:153], v[190:193], v[24:27]
	v_mfma_f32_16x16x32_bf16 v[16:19], v[158:161], v[190:193], v[16:19]
	v_mfma_f32_16x16x32_bf16 v[60:63], v[154:157], v[170:173], v[60:63]
	v_mfma_f32_16x16x32_bf16 v[56:59], v[162:165], v[170:173], v[56:59]
	v_mfma_f32_16x16x32_bf16 v[52:55], v[154:157], v[178:181], v[52:55]
	v_mfma_f32_16x16x32_bf16 v[48:51], v[162:165], v[178:181], v[48:51]
	v_mfma_f32_16x16x32_bf16 v[40:43], v[154:157], v[186:189], v[40:43]
	v_mfma_f32_16x16x32_bf16 v[32:35], v[162:165], v[186:189], v[32:35]
	v_mfma_f32_16x16x32_bf16 v[24:27], v[154:157], v[194:197], v[24:27]
	v_mfma_f32_16x16x32_bf16 v[16:19], v[162:165], v[194:197], v[16:19]
	s_setprio 0
	s_barrier
	s_add_u32 s30, s30, 0x40080
	s_addc_u32 s31, s31, 0
	s_add_i32 s34, s34, s41
	v_lshl_add_u64 v[150:151], s[30:31], 0, v[130:131]
	s_mov_b32 m0, s34
	s_nop 0
	global_load_lds_dwordx4 v[150:151], off
	v_lshl_add_u64 v[150:151], s[30:31], 0, v[134:135]
	s_add_i32 m0, s34, 0x2000
	s_nop 0
	global_load_lds_dwordx4 v[150:151], off
	s_waitcnt vmcnt(6)
	global_load_dword v242, v240, s[98:99]
	v_add_u32_e32 v240, 0x10000, v240
	s_barrier
	s_setprio 1
	v_mfma_f32_16x16x32_bf16 v[44:47], v[198:201], v[166:169], v[44:47]
	v_mfma_f32_16x16x32_bf16 v[36:39], v[206:209], v[166:169], v[36:39]
	v_mfma_f32_16x16x32_bf16 v[28:31], v[198:201], v[174:177], v[28:31]
	v_mfma_f32_16x16x32_bf16 v[20:23], v[206:209], v[174:177], v[20:23]
	v_mfma_f32_16x16x32_bf16 v[12:15], v[198:201], v[182:185], v[12:15]
	v_mfma_f32_16x16x32_bf16 v[8:11], v[206:209], v[182:185], v[8:11]
	v_mfma_f32_16x16x32_bf16 v[4:7], v[198:201], v[190:193], v[4:7]
	v_mfma_f32_16x16x32_bf16 v[0:3], v[206:209], v[190:193], v[0:3]
	v_mfma_f32_16x16x32_bf16 v[44:47], v[202:205], v[170:173], v[44:47]
	v_mfma_f32_16x16x32_bf16 v[36:39], v[214:217], v[170:173], v[36:39]
	v_mfma_f32_16x16x32_bf16 v[28:31], v[202:205], v[178:181], v[28:31]
	v_mfma_f32_16x16x32_bf16 v[20:23], v[214:217], v[178:181], v[20:23]
	v_mfma_f32_16x16x32_bf16 v[12:15], v[202:205], v[186:189], v[12:15]
	v_mfma_f32_16x16x32_bf16 v[8:11], v[214:217], v[186:189], v[8:11]
	v_mfma_f32_16x16x32_bf16 v[4:7], v[202:205], v[194:197], v[4:7]
	v_mfma_f32_16x16x32_bf16 v[0:3], v[214:217], v[194:197], v[0:3]
	s_setprio 0
	s_add_i32 s60, s60, 2
	s_add_u32 s28, s28, 0x100
	s_addc_u32 s29, s29, 0
	s_add_u32 s58, s58, 0x100
	s_addc_u32 s59, s59, 0
	s_cmp_gt_u32 s60, 13
	s_barrier
.LBB0_847:
	ds_read_b128 v[150:153], v147
	ds_read_b128 v[154:157], v147 offset:1024
	ds_read_b128 v[158:161], v147 offset:2048
	ds_read_b128 v[162:165], v147 offset:3072
	s_add_u32 s30, s28, 0xfffc0080
	s_addc_u32 s31, s29, -1
	s_cmp_eq_u32 s60, 12
	s_cselect_b32 s35, s23, s31
	s_cselect_b32 s34, s56, s30
	s_cselect_b32 s31, s21, s59
	s_cselect_b32 s30, s57, s58
	v_lshl_add_u64 v[198:199], s[28:29], 0, v[136:137]
	s_add_i32 m0, s9, 0xc000
	ds_read_b128 v[166:169], v148
	ds_read_b128 v[170:173], v148 offset:1024
	ds_read_b128 v[174:177], v148 offset:2048
	ds_read_b128 v[178:181], v148 offset:3072
	ds_read_b128 v[182:185], v148 offset:4096
	ds_read_b128 v[186:189], v148 offset:5120
	ds_read_b128 v[190:193], v148 offset:6144
	ds_read_b128 v[194:197], v148 offset:7168
	global_load_lds_dwordx4 v[198:199], off
	v_lshl_add_u64 v[198:199], s[28:29], 0, v[138:139]
	s_add_i32 m0, s9, 0xe000
	s_nop 0
	global_load_lds_dwordx4 v[198:199], off
	s_waitcnt lgkmcnt(8)
	s_barrier
	s_waitcnt lgkmcnt(0)
	s_setprio 1
	s_waitcnt lgkmcnt(0)
	v_mfma_f32_16x16x32_bf16 v[124:127], v[150:153], v[166:169], v[124:127]
	v_mfma_f32_16x16x32_bf16 v[120:123], v[158:161], v[166:169], v[120:123]
	v_mfma_f32_16x16x32_bf16 v[116:119], v[150:153], v[174:177], v[116:119]
	v_mfma_f32_16x16x32_bf16 v[112:115], v[158:161], v[174:177], v[112:115]
	v_mfma_f32_16x16x32_bf16 v[100:103], v[150:153], v[182:185], v[100:103]
	v_mfma_f32_16x16x32_bf16 v[96:99], v[158:161], v[182:185], v[96:99]
	v_mfma_f32_16x16x32_bf16 v[84:87], v[150:153], v[190:193], v[84:87]
	v_mfma_f32_16x16x32_bf16 v[80:83], v[158:161], v[190:193], v[80:83]
	v_mfma_f32_16x16x32_bf16 v[124:127], v[154:157], v[170:173], v[124:127]
	v_mfma_f32_16x16x32_bf16 v[120:123], v[162:165], v[170:173], v[120:123]
	v_mfma_f32_16x16x32_bf16 v[116:119], v[154:157], v[178:181], v[116:119]
	v_mfma_f32_16x16x32_bf16 v[112:115], v[162:165], v[178:181], v[112:115]
	v_mfma_f32_16x16x32_bf16 v[100:103], v[154:157], v[186:189], v[100:103]
	v_mfma_f32_16x16x32_bf16 v[96:99], v[162:165], v[186:189], v[96:99]
	v_mfma_f32_16x16x32_bf16 v[84:87], v[154:157], v[194:197], v[84:87]
	v_mfma_f32_16x16x32_bf16 v[80:83], v[162:165], v[194:197], v[80:83]
	s_setprio 0
	s_barrier
; #define PG8_STAGE(bufoff, gbase, voff) do { _Pragma("unroll") for (int _i = 0; _i < 2; ++_i) \
;         __builtin_amdgcn_global_load_lds((const unsigned*)((const char*)(gbase) + (voff)[_i]), (LAS unsigned*)(lds + (bufoff) + ldsw + _i * 8192), 16, 0, 0); } while (0)
; #define PG8_LDA(dst, b, h) do { _Pragma("unroll") for (int m = 0; m < 4; ++m) _Pragma("unroll") for (int k = 0; k < 2; ++k) dst[m][k] = *(const LAS bf16x8*)(lds + PG8_SA(b, h) + aoff + m * 2048 + k * 1024); } while (0)
; #define PG8_LDB(dst, b, h) do { _Pragma("unroll") for (int n = 0; n < 2; ++n) _Pragma("unroll") for (int k = 0; k < 2; ++k) dst[n][k] = *(const LAS bf16x8*)(lds + PG8_SB(b, h) + boff + n * 2048 + k * 1024); } while (0)
; #define PG8_MMA(ai, bj, At, Bt) do { __builtin_amdgcn_s_setprio(1); _Pragma("unroll") for (int m = 0; m < 4; ++m) _Pragma("unroll") for (int n = 0; n < 2; ++n) _Pragma("unroll") for (int k = 0; k < 2; ++k) \
;         acc[ai][bj][m][n] = __builtin_amdgcn_mfma_f32_16x16x32_bf16(Bt[n][k], At[m][k], acc[ai][bj][m][n], 0, 0, 0); __builtin_amdgcn_s_setprio(0); } while (0)
; #define PG8_WAIT_V(n) asm volatile("s_waitcnt vmcnt(" #n ")" ::: "memory")
; #define PG8_WAIT_L(n) asm volatile("s_waitcnt lgkmcnt(" #n ")" ::: "memory")
; #define PG8_BAR __builtin_amdgcn_s_barrier()
; #define PG8_SCHED __builtin_amdgcn_sched_barrier(0)
; #define PG8_BAR __builtin_amdgcn_s_barrier()
; template <class Epi, bool AFTER = false>
; __device__ __forceinline__ void gemm_phase(LAS unsigned char* lds, const Gemm g, const StaticOrder& S, const Epi& E) {
;     ...
;             PG8_LDB(B1, 0, 1); PG8_STAGE(PG8_SB(0, 0), b2, voffB);
;             PG8_BAR; PG8_WAIT_L(0); PG8_MMA(0, 1, At, B1); PG8_BAR;
;             PG8_LDA(At, 0, 1); PG8_STAGE(PG8_SA(0, 0), a2, voffA);
;             PG8_BAR; PG8_WAIT_L(0); PG8_MMA(1, 0, At, B0); PG8_BAR; PG8_SCHED;
;             PG8_STAGE(PG8_SB(0, 1), b2 + hstep, voffB);
;             PG8_WAIT_V(6); PG8_BAR; PG8_MMA(1, 1, At, B1); PG8_BAR;
;             PG8_LDB(B0, 1, 0); PG8_SCHED; PG8_LDA(At, 1, 0); PG8_STAGE(PG8_SA(0, 1), a2 + hstep, voffA);
;             PG8_WAIT_L(8); PG8_BAR; PG8_WAIT_L(0); PG8_MMA(0, 0, At, B0); PG8_BAR; PG8_SCHED;
;             PG8_LDB(B1, 1, 1); PG8_STAGE(PG8_SB(1, 0), b3, voffB);
;             PG8_BAR; PG8_WAIT_L(0); PG8_MMA(0, 1, At, B1); PG8_BAR;
;             PG8_LDA(At, 1, 1); PG8_STAGE(PG8_SA(1, 0), a3, voffA);
	s_add_i32 s61, s50, s41
	v_lshl_add_u64 v[210:211], s[30:31], 0, v[130:131]
	s_mov_b32 m0, s61
	ds_read_b128 v[198:201], v149
	ds_read_b128 v[202:205], v149 offset:1024
	ds_read_b128 v[206:209], v149 offset:2048
	ds_read_b128 v[214:217], v149 offset:3072
	global_load_lds_dwordx4 v[210:211], off
	v_lshl_add_u64 v[218:219], s[30:31], 0, v[134:135]
	s_add_i32 m0, s61, 0x2000
	s_nop 0
	global_load_lds_dwordx4 v[218:219], off
	s_barrier
	s_waitcnt lgkmcnt(0)
	s_setprio 1
	s_waitcnt lgkmcnt(0)
	v_mfma_f32_16x16x32_bf16 v[108:111], v[198:201], v[166:169], v[108:111]
	v_mfma_f32_16x16x32_bf16 v[104:107], v[206:209], v[166:169], v[104:107]
	v_mfma_f32_16x16x32_bf16 v[92:95], v[198:201], v[174:177], v[92:95]
	v_mfma_f32_16x16x32_bf16 v[88:91], v[206:209], v[174:177], v[88:91]
	v_mfma_f32_16x16x32_bf16 v[76:79], v[198:201], v[182:185], v[76:79]
	v_mfma_f32_16x16x32_bf16 v[72:75], v[206:209], v[182:185], v[72:75]
	v_mfma_f32_16x16x32_bf16 v[68:71], v[198:201], v[190:193], v[68:71]
	v_mfma_f32_16x16x32_bf16 v[64:67], v[206:209], v[190:193], v[64:67]
	v_mfma_f32_16x16x32_bf16 v[108:111], v[202:205], v[170:173], v[108:111]
	v_mfma_f32_16x16x32_bf16 v[104:107], v[214:217], v[170:173], v[104:107]
	v_mfma_f32_16x16x32_bf16 v[92:95], v[202:205], v[178:181], v[92:95]
	v_mfma_f32_16x16x32_bf16 v[88:91], v[214:217], v[178:181], v[88:91]
	v_mfma_f32_16x16x32_bf16 v[76:79], v[202:205], v[186:189], v[76:79]
	v_mfma_f32_16x16x32_bf16 v[72:75], v[214:217], v[186:189], v[72:75]
	v_mfma_f32_16x16x32_bf16 v[68:71], v[202:205], v[194:197], v[68:71]
	v_mfma_f32_16x16x32_bf16 v[64:67], v[214:217], v[194:197], v[64:67]
	s_setprio 0
	s_mov_b32 m0, s9
	v_lshl_add_u64 v[220:221], s[34:35], 0, v[128:129]
	s_barrier
	ds_read_b128 v[166:169], v148 offset:16384
	ds_read_b128 v[170:173], v148 offset:17408
	ds_read_b128 v[174:177], v148 offset:18432
	ds_read_b128 v[178:181], v148 offset:19456
	ds_read_b128 v[182:185], v148 offset:20480
	ds_read_b128 v[186:189], v148 offset:21504
	ds_read_b128 v[190:193], v148 offset:22528
	ds_read_b128 v[194:197], v148 offset:23552
	global_load_lds_dwordx4 v[220:221], off
	v_lshl_add_u64 v[222:223], s[34:35], 0, v[132:133]
	s_mov_b32 m0, s42
	s_nop 0
	global_load_lds_dwordx4 v[222:223], off
	s_barrier
	s_waitcnt lgkmcnt(0)
	s_setprio 1
	s_waitcnt lgkmcnt(0)
	v_mfma_f32_16x16x32_bf16 v[60:63], v[150:153], v[166:169], v[60:63]
	v_mfma_f32_16x16x32_bf16 v[56:59], v[158:161], v[166:169], v[56:59]
	v_mfma_f32_16x16x32_bf16 v[52:55], v[150:153], v[174:177], v[52:55]
	v_mfma_f32_16x16x32_bf16 v[48:51], v[158:161], v[174:177], v[48:51]
	v_mfma_f32_16x16x32_bf16 v[40:43], v[150:153], v[182:185], v[40:43]
	v_mfma_f32_16x16x32_bf16 v[32:35], v[158:161], v[182:185], v[32:35]
	v_mfma_f32_16x16x32_bf16 v[24:27], v[150:153], v[190:193], v[24:27]
	v_mfma_f32_16x16x32_bf16 v[16:19], v[158:161], v[190:193], v[16:19]
	v_mfma_f32_16x16x32_bf16 v[60:63], v[154:157], v[170:173], v[60:63]
	v_mfma_f32_16x16x32_bf16 v[56:59], v[162:165], v[170:173], v[56:59]
	v_mfma_f32_16x16x32_bf16 v[52:55], v[154:157], v[178:181], v[52:55]
	v_mfma_f32_16x16x32_bf16 v[48:51], v[162:165], v[178:181], v[48:51]
	v_mfma_f32_16x16x32_bf16 v[40:43], v[154:157], v[186:189], v[40:43]
	v_mfma_f32_16x16x32_bf16 v[32:35], v[162:165], v[186:189], v[32:35]
	v_mfma_f32_16x16x32_bf16 v[24:27], v[154:157], v[194:197], v[24:27]
	v_mfma_f32_16x16x32_bf16 v[16:19], v[162:165], v[194:197], v[16:19]
	s_setprio 0
	s_barrier
	s_add_u32 s62, s30, 0x40000
	s_addc_u32 s63, s31, 0
	s_add_i32 s61, s51, s41
	v_lshl_add_u64 v[150:151], s[62:63], 0, v[130:131]
	s_mov_b32 m0, s61
	s_nop 0
	global_load_lds_dwordx4 v[150:151], off
	v_lshl_add_u64 v[150:151], s[62:63], 0, v[134:135]
	s_add_i32 m0, s61, 0x2000
	s_nop 0
	global_load_lds_dwordx4 v[150:151], off
	s_waitcnt vmcnt(6)
	global_load_dword v242, v240, s[98:99]
	v_add_u32_e32 v240, 0x10000, v240
	s_barrier
	s_setprio 1
	v_mfma_f32_16x16x32_bf16 v[44:47], v[198:201], v[166:169], v[44:47]
	v_mfma_f32_16x16x32_bf16 v[36:39], v[206:209], v[166:169], v[36:39]
	v_mfma_f32_16x16x32_bf16 v[28:31], v[198:201], v[174:177], v[28:31]
	v_mfma_f32_16x16x32_bf16 v[20:23], v[206:209], v[174:177], v[20:23]
	v_mfma_f32_16x16x32_bf16 v[12:15], v[198:201], v[182:185], v[12:15]
	v_mfma_f32_16x16x32_bf16 v[8:11], v[206:209], v[182:185], v[8:11]
	v_mfma_f32_16x16x32_bf16 v[4:7], v[198:201], v[190:193], v[4:7]
	v_mfma_f32_16x16x32_bf16 v[0:3], v[206:209], v[190:193], v[0:3]
	v_mfma_f32_16x16x32_bf16 v[44:47], v[202:205], v[170:173], v[44:47]
	v_mfma_f32_16x16x32_bf16 v[36:39], v[214:217], v[170:173], v[36:39]
	v_mfma_f32_16x16x32_bf16 v[28:31], v[202:205], v[178:181], v[28:31]
	v_mfma_f32_16x16x32_bf16 v[20:23], v[214:217], v[178:181], v[20:23]
	v_mfma_f32_16x16x32_bf16 v[12:15], v[202:205], v[186:189], v[12:15]
	v_mfma_f32_16x16x32_bf16 v[8:11], v[214:217], v[186:189], v[8:11]
	v_mfma_f32_16x16x32_bf16 v[4:7], v[202:205], v[194:197], v[4:7]
	v_mfma_f32_16x16x32_bf16 v[0:3], v[214:217], v[194:197], v[0:3]
	s_setprio 0
	s_add_i32 s61, 0, 0x18000
	v_add_u32_e32 v162, s61, v145
	s_barrier
	ds_read_b128 v[150:153], v162
	ds_read_b128 v[154:157], v162 offset:1024
	ds_read_b128 v[158:161], v162 offset:2048
	ds_read_b128 v[162:165], v162 offset:3072
	s_add_u32 s34, s34, 0x40000
	s_addc_u32 s35, s35, 0
	s_mov_b32 m0, s43
	v_lshl_add_u64 v[198:199], s[34:35], 0, v[128:129]
	ds_read_b128 v[166:169], v148 offset:32768
	ds_read_b128 v[170:173], v148 offset:33792
	ds_read_b128 v[174:177], v148 offset:34816
	ds_read_b128 v[178:181], v148 offset:35840
	ds_read_b128 v[182:185], v148 offset:36864
	ds_read_b128 v[186:189], v148 offset:37888
	ds_read_b128 v[190:193], v148 offset:38912
	ds_read_b128 v[194:197], v148 offset:39936
	global_load_lds_dwordx4 v[198:199], off
	v_lshl_add_u64 v[198:199], s[34:35], 0, v[132:133]
	s_mov_b32 m0, s44
	s_nop 0
	global_load_lds_dwordx4 v[198:199], off
	s_waitcnt lgkmcnt(8)
	s_barrier
; #define PG8_STAGE(bufoff, gbase, voff) do { _Pragma("unroll") for (int _i = 0; _i < 2; ++_i) \
;         __builtin_amdgcn_global_load_lds((const unsigned*)((const char*)(gbase) + (voff)[_i]), (LAS unsigned*)(lds + (bufoff) + ldsw + _i * 8192), 16, 0, 0); } while (0)
; #define PG8_LDA(dst, b, h) do { _Pragma("unroll") for (int m = 0; m < 4; ++m) _Pragma("unroll") for (int k = 0; k < 2; ++k) dst[m][k] = *(const LAS bf16x8*)(lds + PG8_SA(b, h) + aoff + m * 2048 + k * 1024); } while (0)
; #define PG8_LDB(dst, b, h) do { _Pragma("unroll") for (int n = 0; n < 2; ++n) _Pragma("unroll") for (int k = 0; k < 2; ++k) dst[n][k] = *(const LAS bf16x8*)(lds + PG8_SB(b, h) + boff + n * 2048 + k * 1024); } while (0)
; #define PG8_MMA(ai, bj, At, Bt) do { __builtin_amdgcn_s_setprio(1); _Pragma("unroll") for (int m = 0; m < 4; ++m) _Pragma("unroll") for (int n = 0; n < 2; ++n) _Pragma("unroll") for (int k = 0; k < 2; ++k) \
;         acc[ai][bj][m][n] = __builtin_amdgcn_mfma_f32_16x16x32_bf16(Bt[n][k], At[m][k], acc[ai][bj][m][n], 0, 0, 0); __builtin_amdgcn_s_setprio(0); } while (0)
; #define PG8_WAIT_V(n) asm volatile("s_waitcnt vmcnt(" #n ")" ::: "memory")
; #define PG8_WAIT_L(n) asm volatile("s_waitcnt lgkmcnt(" #n ")" ::: "memory")
; #define PG8_BAR __builtin_amdgcn_s_barrier()
; #define PG8_SCHED __builtin_amdgcn_sched_barrier(0)
; #define PG8_LDA(dst, b, h) do { _Pragma("unroll") for (int m = 0; m < 4; ++m) _Pragma("unroll") for (int k = 0; k < 2; ++k) dst[m][k] = *(const LAS bf16x8*)(lds + PG8_SA(b, h) + aoff + m * 2048 + k * 1024); } while (0)
; #define PG8_WAIT_V(n) asm volatile("s_waitcnt vmcnt(" #n ")" ::: "memory")
; #define PG8_WAIT_L(n) asm volatile("s_waitcnt lgkmcnt(" #n ")" ::: "memory")
; template <class Epi, bool AFTER = false>
; __device__ __forceinline__ void gemm_phase(LAS unsigned char* lds, const Gemm g, const StaticOrder& S, const Epi& E) {
;     ...
;             PG8_WAIT_L(8); PG8_BAR; PG8_WAIT_L(0); PG8_MMA(0, 0, At, B0); PG8_BAR; PG8_SCHED;
;             PG8_LDB(B1, 1, 1); PG8_STAGE(PG8_SB(1, 0), b3, voffB);
;             PG8_BAR; PG8_WAIT_L(0); PG8_MMA(0, 1, At, B1); PG8_BAR;
;             PG8_LDA(At, 1, 1); PG8_STAGE(PG8_SA(1, 0), a3, voffA);
;             PG8_BAR; PG8_WAIT_L(0); PG8_MMA(1, 0, At, B0); PG8_BAR; PG8_SCHED;
;             PG8_STAGE(PG8_SB(1, 1), b3 + hstep, voffB);
;             PG8_WAIT_V(6); PG8_BAR; PG8_MMA(1, 1, At, B1); PG8_BAR;
	s_waitcnt lgkmcnt(0)
	s_setprio 1
	s_waitcnt lgkmcnt(0)
	v_mfma_f32_16x16x32_bf16 v[124:127], v[150:153], v[166:169], v[124:127]
	v_mfma_f32_16x16x32_bf16 v[120:123], v[158:161], v[166:169], v[120:123]
	v_mfma_f32_16x16x32_bf16 v[116:119], v[150:153], v[174:177], v[116:119]
	v_mfma_f32_16x16x32_bf16 v[112:115], v[158:161], v[174:177], v[112:115]
	v_mfma_f32_16x16x32_bf16 v[100:103], v[150:153], v[182:185], v[100:103]
	v_mfma_f32_16x16x32_bf16 v[96:99], v[158:161], v[182:185], v[96:99]
	v_mfma_f32_16x16x32_bf16 v[84:87], v[150:153], v[190:193], v[84:87]
	v_mfma_f32_16x16x32_bf16 v[80:83], v[158:161], v[190:193], v[80:83]
	v_mfma_f32_16x16x32_bf16 v[124:127], v[154:157], v[170:173], v[124:127]
	v_mfma_f32_16x16x32_bf16 v[120:123], v[162:165], v[170:173], v[120:123]
	v_mfma_f32_16x16x32_bf16 v[116:119], v[154:157], v[178:181], v[116:119]
	v_mfma_f32_16x16x32_bf16 v[112:115], v[162:165], v[178:181], v[112:115]
	v_mfma_f32_16x16x32_bf16 v[100:103], v[154:157], v[186:189], v[100:103]
	v_mfma_f32_16x16x32_bf16 v[96:99], v[162:165], v[186:189], v[96:99]
	v_mfma_f32_16x16x32_bf16 v[84:87], v[154:157], v[194:197], v[84:87]
	v_mfma_f32_16x16x32_bf16 v[80:83], v[162:165], v[194:197], v[80:83]
	s_setprio 0
	s_barrier
	s_add_i32 s34, 0, 0x1c000
	s_add_i32 s35, s61, s41
	v_add_u32_e32 v213, s34, v145
	v_lshl_add_u64 v[210:211], v[210:211], 0, s[10:11]
	s_mov_b32 m0, s35
	ds_read_b128 v[198:201], v213
	ds_read_b128 v[202:205], v213 offset:1024
	ds_read_b128 v[206:209], v213 offset:2048
	ds_read_b128 v[214:217], v213 offset:3072
	global_load_lds_dwordx4 v[210:211], off
	v_lshl_add_u64 v[210:211], v[218:219], 0, s[10:11]
	s_add_i32 m0, s35, 0x2000
	s_nop 0
	global_load_lds_dwordx4 v[210:211], off
	s_barrier
	s_waitcnt lgkmcnt(0)
	s_setprio 1
	s_waitcnt lgkmcnt(0)
	v_mfma_f32_16x16x32_bf16 v[108:111], v[198:201], v[166:169], v[108:111]
	v_mfma_f32_16x16x32_bf16 v[104:107], v[206:209], v[166:169], v[104:107]
	v_mfma_f32_16x16x32_bf16 v[92:95], v[198:201], v[174:177], v[92:95]
	v_mfma_f32_16x16x32_bf16 v[88:91], v[206:209], v[174:177], v[88:91]
	v_mfma_f32_16x16x32_bf16 v[76:79], v[198:201], v[182:185], v[76:79]
	v_mfma_f32_16x16x32_bf16 v[72:75], v[206:209], v[182:185], v[72:75]
	v_mfma_f32_16x16x32_bf16 v[68:71], v[198:201], v[190:193], v[68:71]
	v_mfma_f32_16x16x32_bf16 v[64:67], v[206:209], v[190:193], v[64:67]
	v_mfma_f32_16x16x32_bf16 v[108:111], v[202:205], v[170:173], v[108:111]
	v_mfma_f32_16x16x32_bf16 v[104:107], v[214:217], v[170:173], v[104:107]
	v_mfma_f32_16x16x32_bf16 v[92:95], v[202:205], v[178:181], v[92:95]
	v_mfma_f32_16x16x32_bf16 v[88:91], v[214:217], v[178:181], v[88:91]
	v_mfma_f32_16x16x32_bf16 v[76:79], v[202:205], v[186:189], v[76:79]
	v_mfma_f32_16x16x32_bf16 v[72:75], v[214:217], v[186:189], v[72:75]
	v_mfma_f32_16x16x32_bf16 v[68:71], v[202:205], v[194:197], v[68:71]
	v_mfma_f32_16x16x32_bf16 v[64:67], v[214:217], v[194:197], v[64:67]
	s_setprio 0
	s_mov_b32 m0, s46
	v_lshl_add_u64 v[210:211], v[220:221], 0, s[10:11]
	s_barrier
	ds_read_b128 v[166:169], v148 offset:49152
	ds_read_b128 v[170:173], v148 offset:50176
	ds_read_b128 v[174:177], v148 offset:51200
	ds_read_b128 v[178:181], v148 offset:52224
	ds_read_b128 v[182:185], v148 offset:53248
	ds_read_b128 v[186:189], v148 offset:54272
	ds_read_b128 v[190:193], v148 offset:55296
	ds_read_b128 v[194:197], v148 offset:56320
	global_load_lds_dwordx4 v[210:211], off
	v_lshl_add_u64 v[210:211], v[222:223], 0, s[10:11]
	s_mov_b32 m0, s47
	s_nop 0
	global_load_lds_dwordx4 v[210:211], off
	s_barrier
	s_waitcnt lgkmcnt(0)
	s_setprio 1
	s_waitcnt lgkmcnt(0)
	v_mfma_f32_16x16x32_bf16 v[60:63], v[150:153], v[166:169], v[60:63]
	v_mfma_f32_16x16x32_bf16 v[56:59], v[158:161], v[166:169], v[56:59]
	v_mfma_f32_16x16x32_bf16 v[52:55], v[150:153], v[174:177], v[52:55]
	v_mfma_f32_16x16x32_bf16 v[48:51], v[158:161], v[174:177], v[48:51]
	v_mfma_f32_16x16x32_bf16 v[40:43], v[150:153], v[182:185], v[40:43]
	v_mfma_f32_16x16x32_bf16 v[32:35], v[158:161], v[182:185], v[32:35]
	v_mfma_f32_16x16x32_bf16 v[24:27], v[150:153], v[190:193], v[24:27]
	v_mfma_f32_16x16x32_bf16 v[16:19], v[158:161], v[190:193], v[16:19]
	v_mfma_f32_16x16x32_bf16 v[60:63], v[154:157], v[170:173], v[60:63]
	v_mfma_f32_16x16x32_bf16 v[56:59], v[162:165], v[170:173], v[56:59]
	v_mfma_f32_16x16x32_bf16 v[52:55], v[154:157], v[178:181], v[52:55]
	v_mfma_f32_16x16x32_bf16 v[48:51], v[162:165], v[178:181], v[48:51]
	v_mfma_f32_16x16x32_bf16 v[40:43], v[154:157], v[186:189], v[40:43]
	v_mfma_f32_16x16x32_bf16 v[32:35], v[162:165], v[186:189], v[32:35]
	v_mfma_f32_16x16x32_bf16 v[24:27], v[154:157], v[194:197], v[24:27]
	v_mfma_f32_16x16x32_bf16 v[16:19], v[162:165], v[194:197], v[16:19]
	s_setprio 0
	s_barrier
	s_add_u32 s30, s30, 0x40080
	s_addc_u32 s31, s31, 0
	s_add_i32 s34, s34, s41
	v_lshl_add_u64 v[150:151], s[30:31], 0, v[130:131]
	s_mov_b32 m0, s34
	s_nop 0
	global_load_lds_dwordx4 v[150:151], off
	v_lshl_add_u64 v[150:151], s[30:31], 0, v[134:135]
	s_add_i32 m0, s34, 0x2000
	s_nop 0
	global_load_lds_dwordx4 v[150:151], off
	s_waitcnt vmcnt(6)
	global_load_dword v242, v240, s[98:99]
	v_add_u32_e32 v240, 0x10000, v240
	s_barrier
; #define PG8_MMA(ai, bj, At, Bt) do { __builtin_amdgcn_s_setprio(1); _Pragma("unroll") for (int m = 0; m < 4; ++m) _Pragma("unroll") for (int n = 0; n < 2; ++n) _Pragma("unroll") for (int k = 0; k < 2; ++k) \
;         acc[ai][bj][m][n] = __builtin_amdgcn_mfma_f32_16x16x32_bf16(Bt[n][k], At[m][k], acc[ai][bj][m][n], 0, 0, 0); __builtin_amdgcn_s_setprio(0); } while (0)
; #define PG8_WAIT_V(n) asm volatile("s_waitcnt vmcnt(" #n ")" ::: "memory")
; #define PG8_BAR __builtin_amdgcn_s_barrier()
; #define PG8_MMA(ai, bj, At, Bt) do { __builtin_amdgcn_s_setprio(1); _Pragma("unroll") for (int m = 0; m < 4; ++m) _Pragma("unroll") for (int n = 0; n < 2; ++n) _Pragma("unroll") for (int k = 0; k < 2; ++k) \
;         acc[ai][bj][m][n] = __builtin_amdgcn_mfma_f32_16x16x32_bf16(Bt[n][k], At[m][k], acc[ai][bj][m][n], 0, 0, 0); __builtin_amdgcn_s_setprio(0); } while (0)
; #define PG8_WAIT_V(n) asm volatile("s_waitcnt vmcnt(" #n ")" ::: "memory")
; #define PG8_BAR __builtin_amdgcn_s_barrier()
; template <class Epi, bool AFTER = false>
; __device__ __forceinline__ void gemm_phase(LAS unsigned char* lds, const Gemm g, const StaticOrder& S, const Epi& E) {
;     ...
;             PG8_WAIT_V(6); PG8_BAR; PG8_MMA(1, 1, At, B1); PG8_BAR;
;         }
;         if constexpr (!AFTER) E(acc, cur, wr, wc, fr, fq);
;         if (!has_next) break;
	s_setprio 1
	v_mfma_f32_16x16x32_bf16 v[44:47], v[198:201], v[166:169], v[44:47]
	v_mfma_f32_16x16x32_bf16 v[36:39], v[206:209], v[166:169], v[36:39]
	v_mfma_f32_16x16x32_bf16 v[28:31], v[198:201], v[174:177], v[28:31]
	v_mfma_f32_16x16x32_bf16 v[20:23], v[206:209], v[174:177], v[20:23]
	v_mfma_f32_16x16x32_bf16 v[12:15], v[198:201], v[182:185], v[12:15]
	v_mfma_f32_16x16x32_bf16 v[8:11], v[206:209], v[182:185], v[8:11]
	v_mfma_f32_16x16x32_bf16 v[4:7], v[198:201], v[190:193], v[4:7]
	v_mfma_f32_16x16x32_bf16 v[0:3], v[206:209], v[190:193], v[0:3]
	v_mfma_f32_16x16x32_bf16 v[44:47], v[202:205], v[170:173], v[44:47]
	v_mfma_f32_16x16x32_bf16 v[36:39], v[214:217], v[170:173], v[36:39]
	v_mfma_f32_16x16x32_bf16 v[28:31], v[202:205], v[178:181], v[28:31]
	v_mfma_f32_16x16x32_bf16 v[20:23], v[214:217], v[178:181], v[20:23]
	v_mfma_f32_16x16x32_bf16 v[12:15], v[202:205], v[186:189], v[12:15]
	v_mfma_f32_16x16x32_bf16 v[8:11], v[214:217], v[186:189], v[8:11]
	v_mfma_f32_16x16x32_bf16 v[4:7], v[202:205], v[194:197], v[4:7]
	v_mfma_f32_16x16x32_bf16 v[0:3], v[214:217], v[194:197], v[0:3]
	s_setprio 0
	s_add_i32 s60, s60, 2
	s_add_u32 s28, s28, 0x100
	s_addc_u32 s29, s29, 0
	s_add_u32 s58, s58, 0x100
	s_addc_u32 s59, s59, 0
	s_cmp_gt_u32 s60, 13
	s_barrier
	s_cbranch_scc0 .LBB0_847
	v_lshl_add_u32 v152, s8, 8, v144
	v_lshl_or_b32 v150, s55, 8, v146
	v_ashrrev_i32_e32 v153, 31, v152
	v_ashrrev_i32_e32 v151, 31, v150
	v_lshlrev_b64 v[154:155], 12, v[152:153]
	v_lshl_add_u64 v[154:155], s[4:5], 0, v[154:155]
	v_lshlrev_b64 v[150:151], 2, v[150:151]
	v_lshl_add_u64 v[154:155], v[154:155], 0, v[150:151]
	global_store_dwordx4 v[154:155], v[124:127], off
	global_store_dwordx4 v[154:155], v[120:123], off offset:16
	global_store_dwordx4 v[154:155], v[108:111], off offset:512
	global_store_dwordx4 v[154:155], v[104:107], off offset:528
	s_mov_b32 s55, s20
	s_mov_b32 s8, s22
	v_or_b32_e32 v104, 16, v152
	v_ashrrev_i32_e32 v105, 31, v104
	v_lshlrev_b64 v[104:105], 12, v[104:105]
	v_lshl_add_u64 v[104:105], s[4:5], 0, v[104:105]
	v_lshl_add_u64 v[104:105], v[104:105], 0, v[150:151]
	global_store_dwordx4 v[104:105], v[116:119], off
	global_store_dwordx4 v[104:105], v[112:115], off offset:16
	global_store_dwordx4 v[104:105], v[92:95], off offset:512
	global_store_dwordx4 v[104:105], v[88:91], off offset:528
	s_mov_b64 s[30:31], s[26:27]
	s_mov_b64 s[28:29], s[24:25]
	v_or_b32_e32 v88, 32, v152
	v_ashrrev_i32_e32 v89, 31, v88
	v_lshlrev_b64 v[88:89], 12, v[88:89]
	v_lshl_add_u64 v[88:89], s[4:5], 0, v[88:89]
	v_lshl_add_u64 v[88:89], v[88:89], 0, v[150:151]
	global_store_dwordx4 v[88:89], v[100:103], off
	global_store_dwordx4 v[88:89], v[96:99], off offset:16
	global_store_dwordx4 v[88:89], v[76:79], off offset:512
	global_store_dwordx4 v[88:89], v[72:75], off offset:528
	s_nop 1
	v_or_b32_e32 v72, 48, v152
	v_ashrrev_i32_e32 v73, 31, v72
	v_lshlrev_b64 v[72:73], 12, v[72:73]
	v_lshl_add_u64 v[72:73], s[4:5], 0, v[72:73]
	v_lshl_add_u64 v[72:73], v[72:73], 0, v[150:151]
	global_store_dwordx4 v[72:73], v[84:87], off
	global_store_dwordx4 v[72:73], v[80:83], off offset:16
	global_store_dwordx4 v[72:73], v[68:71], off offset:512
	global_store_dwordx4 v[72:73], v[64:67], off offset:528
	s_nop 1
	v_add_co_u32_e32 v66, vcc, s52, v154
	v_lshl_add_u64 v[64:65], v[154:155], 0, s[12:13]
	s_nop 0
	v_addc_co_u32_e32 v67, vcc, 0, v155, vcc
	global_store_dwordx4 v[66:67], v[60:63], off
	global_store_dwordx4 v[64:65], v[56:59], off offset:16
	global_store_dwordx4 v[64:65], v[44:47], off offset:512
	global_store_dwordx4 v[64:65], v[36:39], off offset:528
	s_nop 1
	v_add_co_u32_e32 v38, vcc, s53, v154
	v_lshl_add_u64 v[36:37], v[154:155], 0, s[14:15]
	s_nop 0
	v_addc_co_u32_e32 v39, vcc, 0, v155, vcc
	global_store_dwordx4 v[38:39], v[52:55], off
	global_store_dwordx4 v[36:37], v[48:51], off offset:16
	global_store_dwordx4 v[36:37], v[28:31], off offset:512
	global_store_dwordx4 v[36:37], v[20:23], off offset:528
	s_nop 1
	v_add_co_u32_e32 v22, vcc, s54, v154
	v_lshl_add_u64 v[20:21], v[154:155], 0, s[16:17]
	s_nop 0
	v_addc_co_u32_e32 v23, vcc, 0, v155, vcc
	global_store_dwordx4 v[22:23], v[40:43], off
	global_store_dwordx4 v[20:21], v[32:35], off offset:16
	global_store_dwordx4 v[20:21], v[12:15], off offset:512
	global_store_dwordx4 v[20:21], v[8:11], off offset:528
	s_nop 1
	v_add_co_u32_e32 v10, vcc, 0xb0000, v154
	v_lshl_add_u64 v[8:9], v[154:155], 0, s[18:19]
	s_nop 0
	v_addc_co_u32_e32 v11, vcc, 0, v155, vcc
	s_and_b64 vcc, exec, s[2:3]
	global_store_dwordx4 v[10:11], v[24:27], off
	global_store_dwordx4 v[8:9], v[16:19], off offset:16
	global_store_dwordx4 v[8:9], v[4:7], off offset:512
	global_store_dwordx4 v[8:9], v[0:3], off offset:528
	s_cbranch_vccz .LBB0_840
	s_waitcnt vmcnt(0)
	s_cmpk_gt_u32 s39, 0xff
	s_cbranch_scc1 .LBB0_851
	s_barrier
